# neighbourhood-attention units: the next unit's Q fragments and bias-table word are prefetched into spare VGPRs during the current unit's epilogue (amplified x4 probe: -11..-14 us per natten pass)
# speedup vs baseline: 1.0055x; 1.0055x over previous
.LBB0_993:
	s_cmp_lt_i32 s58, 10
	s_cselect_b64 s[4:5], -1, 0
	s_add_u32 s3, s56, 0x14200000
	s_addc_u32 s29, s57, 0
	s_and_b64 s[12:13], s[4:5], s[0:1]
	s_and_b64 s[0:1], s[12:13], s[70:71]
	s_andn2_b64 vcc, exec, s[0:1]
	s_cbranch_vccnz .LBB0_1088
	v_lshrrev_b32_e32 v0, 5, v192
	v_mov_b32_e32 v80, 0
	v_mul_u32_u24_e32 v0, 31, v0
	v_readlane_b32 s36, v254, 2
	v_add_lshl_u32 v0, v0, v191, 2
	s_waitcnt lgkmcnt(0)
	v_mov_b32_e32 v1, v80
	v_readlane_b32 s42, v254, 8
	v_readlane_b32 s43, v254, 9
	v_and_b32_e32 v100, 24, v203
	v_and_b32_e32 v2, 32, v205
	v_lshl_add_u64 v[102:103], s[42:43], 0, v[0:1]
	v_lshlrev_b32_e32 v0, 10, v201
	v_lshlrev_b32_e32 v1, 4, v191
	v_lshlrev_b32_e32 v4, 4, v192
	v_lshlrev_b32_e32 v3, 8, v201
	v_and_b32_e32 v4, 0xc0, v4
	v_add3_u32 v153, 0, v0, v1
	v_add3_u32 v0, 0, v2, v100
	v_readlane_b32 s0, v254, 18
	v_add3_u32 v154, v0, v3, v4
	v_or_b32_e32 v0, 8, v199
	s_bitcmp1_b32 s0, 6
	v_readlane_b32 s51, v254, 17
	v_lshlrev_b32_e32 v158, 7, v0
	v_lshlrev_b32_e32 v110, 10, v0
	v_or_b32_e32 v0, 16, v199
	s_cselect_b64 s[14:15], -1, 0
	s_movk_i32 s0, 0x1e0
	v_readlane_b32 s48, v254, 14
	v_readlane_b32 s49, v254, 15
	v_readlane_b32 s50, v254, 16
	s_add_i32 s4, 0, 0x18800
	v_lshlrev_b32_e32 v105, 2, v201
	v_lshlrev_b32_e32 v159, 7, v0
	v_lshlrev_b32_e32 v112, 10, v0
	v_or_b32_e32 v0, 24, v199
	v_readlane_b32 s51, v254, 0
	v_cmp_gt_u32_e64 s[0:1], s0, v192
	v_cmp_ne_u32_e64 s[8:9], 31, v191
	s_mov_b32 s19, 0
	v_lshl_add_u32 v101, v192, 2, s4
	v_lshlrev_b32_e32 v104, 3, v201
	v_or_b32_e32 v107, 32, v105
	v_or_b32_e32 v109, 33, v105
	v_or_b32_e32 v111, 34, v105
	v_or_b32_e32 v113, 35, v105
	v_or_b32_e32 v115, 40, v105
	v_or_b32_e32 v138, 41, v105
	v_or_b32_e32 v139, 42, v105
	v_or_b32_e32 v140, 43, v105
	v_or_b32_e32 v141, 48, v105
	v_or_b32_e32 v142, 49, v105
	v_or_b32_e32 v143, 50, v105
	v_or_b32_e32 v144, 51, v105
	v_or_b32_e32 v145, 24, v105
	v_or_b32_e32 v146, 56, v105
	v_or_b32_e32 v147, 25, v105
	v_or_b32_e32 v148, 57, v105
	v_or_b32_e32 v149, 26, v105
	v_or_b32_e32 v150, 58, v105
	v_or_b32_e32 v151, 27, v105
	v_or_b32_e32 v152, 59, v105
	v_cmp_gt_u32_e64 s[4:5], 32, v190
	v_lshlrev_b32_e32 v155, 4, v201
	v_lshlrev_b32_e32 v156, 9, v201
	v_and_b32_e32 v106, 56, v203
	v_lshlrev_b32_e32 v157, 7, v199
	v_lshlrev_b32_e32 v108, 10, v199
	v_lshlrev_b32_e32 v160, 7, v0
	v_lshlrev_b32_e32 v114, 10, v0
	v_or_b32_e32 v161, 1, v105
	v_or_b32_e32 v162, 2, v105
	v_or_b32_e32 v163, 3, v105
	v_or_b32_e32 v164, 8, v105
	v_or_b32_e32 v165, 9, v105
	v_or_b32_e32 v166, 10, v105
	v_or_b32_e32 v167, 11, v105
	v_or_b32_e32 v168, 16, v105
	v_or_b32_e32 v169, 17, v105
	v_or_b32_e32 v170, 18, v105
	v_or_b32_e32 v171, 19, v105
	s_mov_b32 s30, 0xff800000
	s_mov_b64 s[20:21], 0x4000
	s_add_i32 s31, 0, 0x18c00
	s_movk_i32 s33, 0xe000
	s_mov_b32 s48, 0x41000000
	s_mov_b32 s49, 0x42fc0000
	v_mov_b32_e32 v172, 0x7c
	v_mov_b32_e32 v173, 0x42800000
	v_not_b32_e32 v174, 63
	s_mov_b32 s101, 0
	s_mov_b32 s50, s51
	v_readlane_b32 s37, v254, 3
	v_readlane_b32 s38, v254, 4
	v_readlane_b32 s39, v254, 5
	v_readlane_b32 s40, v254, 6
	v_readlane_b32 s41, v254, 7
	v_readlane_b32 s44, v254, 10
	v_readlane_b32 s45, v254, 11
	v_readlane_b32 s46, v254, 12
	v_readlane_b32 s47, v254, 13
	s_branch .LBB0_997

.LBB0_1005:
	s_and_saveexec_b64 s[42:43], s[0:1]
	s_cbranch_execz .LBB0_1009
	v_mov_b32_e32 v0, 0xff800000
	s_and_saveexec_b64 s[44:45], s[8:9]
	s_cbranch_execz .LBB0_1008
	s_lshl_b32 s80, s78, 2
	s_mov_b32 s81, s19
	v_lshl_add_u64 v[0:1], v[102:103], 0, s[80:81]
	s_cmp_eq_u32 s101, 1
	s_cbranch_scc1 .Lnp1_r
	global_load_dword v0, v[0:1], off
	s_branch .Lnp1_rj
.Lnp1_r:
	s_waitcnt vmcnt(0)
	v_mov_b32_e32 v0, v252
.Lnp1_rj:
	s_waitcnt vmcnt(0)
	v_mul_f32_e32 v0, 0x3fb8aa3b, v0

.LBB0_1009:
	s_or_b64 exec, exec, s[42:43]
	s_lshl_b32 s80, s79, 5
	v_or_b32_e32 v0, s65, v191
	v_add_u32_e32 v0, s80, v0
	v_add_u32_e32 v2, s64, v0
	v_mov_b32_e32 v3, v80
	v_lshlrev_b64 v[2:3], 7, v[2:3]
	v_lshl_add_u64 v[2:3], s[36:37], 0, v[2:3]
	v_lshlrev_b32_e32 v4, 1, v104
	v_mov_b32_e32 v5, v80
	v_lshl_add_u64 v[2:3], v[2:3], 0, v[4:5]
	s_cmp_eq_u32 s101, 1
	s_cbranch_scc1 .Lnp1_q
	global_load_dwordx4 v[84:87], v[2:3], off
	global_load_dwordx4 v[88:91], v[2:3], off offset:32
	global_load_dwordx4 v[92:95], v[2:3], off offset:64
	global_load_dwordx4 v[96:99], v[2:3], off offset:96
	s_branch .Lnp1_qj
.Lnp1_q:
	s_waitcnt vmcnt(0)
	v_mov_b32_e32 v84, v236
	v_mov_b32_e32 v85, v237
	v_mov_b32_e32 v86, v238
	v_mov_b32_e32 v87, v239
	v_mov_b32_e32 v88, v240
	v_mov_b32_e32 v89, v241
	v_mov_b32_e32 v90, v242
	v_mov_b32_e32 v91, v243
	v_mov_b32_e32 v92, v244
	v_mov_b32_e32 v93, v245
	v_mov_b32_e32 v94, v246
	v_mov_b32_e32 v95, v247
	v_mov_b32_e32 v96, v248
	v_mov_b32_e32 v97, v249
	v_mov_b32_e32 v98, v250
	v_mov_b32_e32 v99, v251
.Lnp1_qj:
	s_lshl_b32 s42, s79, 10
	s_add_i32 s82, s42, 0
	s_lshl_b32 s41, s79, 3
	s_add_i32 s81, s82, 0xc000
	s_waitcnt vmcnt(0) lgkmcnt(0)
	s_barrier
	s_cmp_ge_u32 s77, s71
	v_readfirstlane_b32 s44, v0
	s_cselect_b64 s[42:43], -1, 0
	s_cmp_lt_u32 s77, s71
	s_cbranch_scc0 .LBB0_1011
	s_lshl_b32 s45, s76, 13
	s_or_b32 s84, s45, 0x2000
	s_mov_b32 s85, s19
	v_lshl_add_u64 v[2:3], v[34:35], 0, s[84:85]
	s_add_i32 s45, s82, 0xa000
	s_mov_b32 m0, s45
	s_nop 0
	global_load_lds_dwordx4 v[2:3], off
	v_lshl_add_u64 v[2:3], v[36:37], 0, s[84:85]
	s_add_i32 s45, s81, 0xa000
	s_mov_b32 m0, s45
	s_nop 0
	global_load_lds_dwordx4 v[2:3], off

.LBB0_1027:
	s_and_b64 vcc, exec, s[24:25]
	s_cbranch_vccz .LBB0_1034
	v_readfirstlane_b32 s100, v192
	s_bfe_u32 s98, s51, 0x40005
	s_mulk_i32 s98, 0x1d1
	s_lshl_b32 s98, s98, 2
	s_mov_b32 s99, 0
	v_lshl_add_u64 v[234:235], v[102:103], 0, s[98:99]
	s_mov_b64 s[98:99], exec
	s_and_b64 exec, exec, s[0:1]
	s_and_b64 exec, exec, s[8:9]
	global_load_dword v252, v[234:235], off
	s_mov_b64 exec, s[98:99]
	s_lshr_b32 s100, s100, 6
	s_lshl_b32 s100, s100, 5
	s_and_b32 s98, s51, 31
	s_lshl_b32 s98, s98, 8
	s_add_i32 s100, s100, s98
	s_add_i32 s100, s100, s72
	v_add_u32_e32 v234, s100, v191
	v_mov_b32_e32 v235, v80
	v_lshlrev_b64 v[234:235], 7, v[234:235]
	s_sub_u32 s98, s34, 0x4000000
	s_subb_u32 s99, s35, 0
	v_lshl_add_u64 v[234:235], s[98:99], 0, v[234:235]
	v_lshlrev_b32_e32 v232, 1, v104
	v_mov_b32_e32 v233, v80
	v_lshl_add_u64 v[234:235], v[234:235], 0, v[232:233]
	global_load_dwordx4 v[236:239], v[234:235], off
	global_load_dwordx4 v[240:243], v[234:235], off offset:32
	global_load_dwordx4 v[244:247], v[234:235], off offset:64
	global_load_dwordx4 v[248:251], v[234:235], off offset:96
	s_mov_b32 s101, 1
	v_or_b32_e32 v34, s72, v175
	v_or_b32_e32 v32, s72, v190
	v_lshlrev_b32_e32 v34, 7, v34
	v_mov_b32_e32 v35, v80
	v_lshlrev_b32_e32 v32, 7, v32
	v_mov_b32_e32 v33, v80
	s_lshl_b32 s42, s41, 1
	v_lshl_add_u64 v[34:35], s[26:27], 0, v[34:35]
	s_mov_b32 s41, s19
	v_lshl_add_u64 v[32:33], s[34:35], 0, v[32:33]
	s_mov_b32 s43, s19
	v_lshl_add_u64 v[34:35], v[34:35], 0, s[40:41]
	v_mov_b32_e32 v117, v80
	v_lshl_add_u64 v[32:33], v[32:33], 0, s[42:43]
	s_cmp_gt_i32 s69, s68
	v_lshl_add_u64 v[34:35], v[34:35], 0, v[116:117]
	s_cbranch_scc0 .LBB0_1077
	s_cmp_ge_i32 s69, s68
	s_cbranch_scc0 .LBB0_1078

.LBB0_1043:
	s_and_saveexec_b64 s[6:7], s[0:1]
	s_cbranch_execz .LBB0_1047
	v_mov_b32_e32 v0, 0xff800000
	s_and_saveexec_b64 s[40:41], s[8:9]
	s_cbranch_execz .LBB0_1046
	s_lshl_b32 s44, s78, 2
	s_mov_b32 s45, s19
	v_lshl_add_u64 v[0:1], v[102:103], 0, s[44:45]
	s_cmp_eq_u32 s101, 1
	s_cbranch_scc1 .Lnp2_r
	global_load_dword v0, v[0:1], off
	s_branch .Lnp2_rj

.LBB0_1047:
	s_or_b64 exec, exec, s[6:7]
	s_lshl_b32 s43, s42, 5
	v_or_b32_e32 v0, s65, v191
	v_add_u32_e32 v0, s43, v0
	v_add_u32_e32 v2, s64, v0
	v_mov_b32_e32 v3, v80
	v_lshlrev_b64 v[2:3], 7, v[2:3]
	v_lshl_add_u64 v[2:3], s[36:37], 0, v[2:3]
	v_lshlrev_b32_e32 v4, 1, v104
	v_mov_b32_e32 v5, v80
	v_lshl_add_u64 v[2:3], v[2:3], 0, v[4:5]
	s_cmp_eq_u32 s101, 1
	s_cbranch_scc1 .Lnp2_q
	global_load_dwordx4 v[82:85], v[2:3], off
	global_load_dwordx4 v[86:89], v[2:3], off offset:32
	global_load_dwordx4 v[90:93], v[2:3], off offset:64
	global_load_dwordx4 v[94:97], v[2:3], off offset:96
	s_branch .Lnp2_qj
.Lnp2_q:
	s_waitcnt vmcnt(0)
	v_mov_b32_e32 v82, v236
	v_mov_b32_e32 v83, v237
	v_mov_b32_e32 v84, v238
	v_mov_b32_e32 v85, v239
	v_mov_b32_e32 v86, v240
	v_mov_b32_e32 v87, v241
	v_mov_b32_e32 v88, v242
	v_mov_b32_e32 v89, v243
	v_mov_b32_e32 v90, v244
	v_mov_b32_e32 v91, v245
	v_mov_b32_e32 v92, v246
	v_mov_b32_e32 v93, v247
	v_mov_b32_e32 v94, v248
	v_mov_b32_e32 v95, v249
	v_mov_b32_e32 v96, v250
	v_mov_b32_e32 v97, v251
.Lnp2_qj:
	s_lshl_b32 s6, s42, 10
	s_add_i32 s45, s6, 0
	s_lshl_b32 s39, s42, 3
	s_add_i32 s44, s45, 0xc000
	s_waitcnt vmcnt(0) lgkmcnt(0)
	s_barrier
	s_cmp_ge_u32 s77, s71
	v_readfirstlane_b32 s36, v0
	s_cselect_b64 s[6:7], -1, 0
	s_cmp_lt_u32 s77, s71
	s_cbranch_scc0 .LBB0_1049
	s_lshl_b32 s37, s76, 13
	s_or_b32 s40, s37, 0x2000
	s_mov_b32 s41, s19
	v_lshl_add_u64 v[2:3], v[34:35], 0, s[40:41]
	s_add_i32 s37, s45, 0xa000
	s_mov_b32 m0, s37
	s_nop 0
	global_load_lds_dwordx4 v[2:3], off
	v_lshl_add_u64 v[2:3], v[36:37], 0, s[40:41]
	s_add_i32 s37, s44, 0xa000
	s_mov_b32 m0, s37
	s_nop 0
	global_load_lds_dwordx4 v[2:3], off

.LBB0_1065:
	s_and_b64 vcc, exec, s[24:25]
	s_cbranch_vccz .LBB0_1072
	v_readfirstlane_b32 s100, v192
	s_bfe_u32 s98, s51, 0x40005
	s_mulk_i32 s98, 0x1d1
	s_lshl_b32 s98, s98, 2
	s_mov_b32 s99, 0
	v_lshl_add_u64 v[234:235], v[102:103], 0, s[98:99]
	s_mov_b64 s[98:99], exec
	s_and_b64 exec, exec, s[0:1]
	s_and_b64 exec, exec, s[8:9]
	global_load_dword v252, v[234:235], off
	s_mov_b64 exec, s[98:99]
	s_lshr_b32 s100, s100, 6
	s_lshl_b32 s100, s100, 5
	s_and_b32 s98, s51, 31
	s_lshl_b32 s98, s98, 8
	s_add_i32 s100, s100, s98
	s_add_i32 s100, s100, s72
	v_add_u32_e32 v234, s100, v191
	v_mov_b32_e32 v235, v80
	v_lshlrev_b64 v[234:235], 7, v[234:235]
	s_sub_u32 s98, s34, 0x4000000
	s_subb_u32 s99, s35, 0
	v_lshl_add_u64 v[234:235], s[98:99], 0, v[234:235]
	v_lshlrev_b32_e32 v232, 1, v104
	v_mov_b32_e32 v233, v80
	v_lshl_add_u64 v[234:235], v[234:235], 0, v[232:233]
	global_load_dwordx4 v[236:239], v[234:235], off
	global_load_dwordx4 v[240:243], v[234:235], off offset:32
	global_load_dwordx4 v[244:247], v[234:235], off offset:64
	global_load_dwordx4 v[248:251], v[234:235], off offset:96
	s_mov_b32 s101, 1
	v_or_b32_e32 v34, s72, v81
	v_or_b32_e32 v32, s72, v190
	v_lshlrev_b32_e32 v34, 7, v34
	v_mov_b32_e32 v35, v80
	v_lshlrev_b32_e32 v32, 7, v32
	v_mov_b32_e32 v33, v80
	s_lshl_b32 s18, s39, 1
	v_lshl_add_u64 v[34:35], s[26:27], 0, v[34:35]
	s_mov_b32 s39, s19
	v_lshl_add_u64 v[32:33], s[34:35], 0, v[32:33]
	v_lshl_add_u64 v[34:35], v[34:35], 0, s[38:39]
	v_mov_b32_e32 v117, v80
	v_lshl_add_u64 v[32:33], v[32:33], 0, s[18:19]
	s_cmp_gt_i32 s69, s68
	v_lshl_add_u64 v[34:35], v[34:35], 0, v[116:117]
	s_cbranch_scc0 .LBB0_1084
	s_cmp_ge_i32 s69, s68
	s_cbranch_scc0 .LBB0_1085
